# latent attention tile loop: waves 4-7 run the rotated body (P*V of the previous tile first), 4-slot K/V ring
# baseline (speedup 1.0000x reference)
.LBB0_114:
	v_sub_f32_e32 v92, v92, v163
	v_sub_f32_e32 v93, v93, v163
	v_exp_f32_e32 v92, v92
	v_exp_f32_e32 v93, v93
	v_sub_f32_e32 v88, v88, v163
	v_sub_f32_e32 v94, v94, v163
	v_exp_f32_e32 v105, v88
	v_sub_f32_e32 v88, v89, v163
	v_exp_f32_e32 v94, v94
	v_sub_f32_e32 v95, v95, v163
	v_exp_f32_e32 v106, v88
	v_sub_f32_e32 v88, v90, v163
	v_exp_f32_e32 v95, v95
	v_exp_f32_e32 v107, v88
	v_sub_f32_e32 v88, v91, v163
	v_exp_f32_e32 v108, v88
	v_cvt_pk_bf16_f32 v88, v92, v93
	v_add_f32_e32 v92, 0, v92
	v_add_f32_e32 v92, v93, v92
	v_add_f32_e32 v92, v94, v92
	v_sub_f32_e32 v72, v100, v163
	v_add_f32_e32 v92, v95, v92
	v_exp_f32_e32 v100, v72
	v_sub_f32_e32 v72, v101, v163
	v_add_f32_e32 v92, v105, v92
	v_exp_f32_e32 v101, v72
	v_sub_f32_e32 v72, v102, v163
	v_add_f32_e32 v92, v106, v92
	v_exp_f32_e32 v102, v72
	v_sub_f32_e32 v72, v103, v163
	v_add_f32_e32 v92, v107, v92
	v_exp_f32_e32 v103, v72
	v_sub_f32_e32 v72, v96, v163
	v_add_f32_e32 v92, v108, v92
	v_exp_f32_e32 v96, v72
	v_sub_f32_e32 v72, v97, v163
	v_add_f32_e32 v92, v100, v92
	v_exp_f32_e32 v97, v72
	v_sub_f32_e32 v72, v98, v163
	v_add_f32_e32 v92, v101, v92
	v_exp_f32_e32 v98, v72
	v_sub_f32_e32 v72, v99, v163
	v_add_f32_e32 v92, v102, v92
	s_waitcnt lgkmcnt(0)
	v_add_f32_e32 v3, v3, v104
	v_add_f32_e32 v0, v0, v2
	v_exp_f32_e32 v99, v72
	v_add_f32_e32 v92, v103, v92
	v_mul_f32_e32 v3, 0x3fb8aa3b, v3
	v_mul_f32_e32 v0, 0x3fb8aa3b, v0
	v_add_f32_e32 v92, v96, v92
	v_exp_f32_e32 v3, v3
	v_exp_f32_e32 v0, v0
	v_add_f32_e32 v92, v97, v92
	v_add_f32_e32 v2, v98, v92
	v_add_f32_e32 v2, v99, v2
	v_cvt_pk_bf16_f32 v91, v107, v108
	v_add_f32_e32 v108, v141, v2
	v_sub_f32_e32 v2, v3, v0
	v_sub_f32_e32 v0, v84, v161
	v_exp_f32_e32 v0, v0
	v_sub_f32_e32 v3, v85, v161
	v_exp_f32_e32 v3, v3
	v_sub_f32_e32 v84, v86, v161
	v_exp_f32_e32 v84, v84
	v_sub_f32_e32 v85, v87, v161
	v_exp_f32_e32 v85, v85
	v_sub_f32_e32 v80, v80, v161
	v_add_f32_e32 v86, 0, v0
	v_exp_f32_e32 v80, v80
	v_sub_f32_e32 v81, v81, v161
	v_add_f32_e32 v86, v3, v86
	v_exp_f32_e32 v81, v81
	v_sub_f32_e32 v82, v82, v161
	v_add_f32_e32 v86, v84, v86
	v_exp_f32_e32 v82, v82
	v_sub_f32_e32 v83, v83, v161
	v_add_f32_e32 v86, v85, v86
	v_exp_f32_e32 v83, v83
	v_sub_f32_e32 v76, v76, v161
	v_add_f32_e32 v86, v80, v86
	v_exp_f32_e32 v76, v76
	v_sub_f32_e32 v77, v77, v161
	v_add_f32_e32 v86, v81, v86
	v_exp_f32_e32 v77, v77
	v_sub_f32_e32 v78, v78, v161
	v_add_f32_e32 v86, v82, v86
	v_exp_f32_e32 v78, v78
	v_sub_f32_e32 v79, v79, v161
	v_add_f32_e32 v86, v83, v86
	v_exp_f32_e32 v79, v79
	v_sub_f32_e32 v68, v68, v161
	v_add_f32_e32 v86, v76, v86
	v_exp_f32_e32 v87, v68
	v_sub_f32_e32 v68, v69, v161
	v_add_f32_e32 v86, v77, v86
	v_exp_f32_e32 v92, v68
	v_sub_f32_e32 v68, v70, v161
	v_add_f32_e32 v86, v78, v86
	v_exp_f32_e32 v93, v68
	v_sub_f32_e32 v68, v71, v161
	v_cvt_pk_bf16_f32 v89, v94, v95
	v_add_f32_e32 v86, v79, v86
	v_exp_f32_e32 v94, v68
	v_add_f32_e32 v68, v87, v86
	v_add_f32_e32 v68, v92, v68
	v_add_f32_e32 v68, v93, v68
	v_add_f32_e32 v68, v94, v68
	v_add_f32_e32 v109, v140, v68
	v_cvt_pk_bf16_f32 v68, v0, v3
	v_cvt_pk_bf16_f32 v70, v80, v81
	v_add_u32_e32 v0, 0x18000, v117
	ds_read_b64 v[80:81], v0 offset:0
	v_cvt_pk_bf16_f32 v71, v82, v83
	v_add_u32_e32 v3, 0x18000, v137
	ds_read_b64 v[82:83], v3 offset:0
	v_cvt_pk_bf16_f32 v69, v84, v85
	v_add_u32_e32 v110, 0x18000, v138
	ds_read_b64 v[84:85], v110 offset:0
	v_cvt_pk_bf16_f32 v76, v76, v77
	v_cvt_pk_bf16_f32 v77, v78, v79
	v_cvt_pk_bf16_f32 v78, v87, v92
	v_add_u32_e32 v111, 0x18000, v139
	ds_read_b64 v[86:87], v111 offset:0
	v_cvt_pk_bf16_f32 v79, v93, v94
	ds_read_b64 v[92:93], v0 offset:2048
	ds_read_b64 v[94:95], v3 offset:2048
	v_cvt_pk_bf16_f32 v74, v96, v97
	ds_read_b64 v[96:97], v110 offset:2048
	v_cvt_pk_bf16_f32 v75, v98, v99
	ds_read_b64 v[98:99], v111 offset:2048
	v_cvt_pk_bf16_f32 v72, v100, v101
	ds_read_b64 v[100:101], v0 offset:4096
	v_cvt_pk_bf16_f32 v73, v102, v103
	ds_read_b64 v[102:103], v3 offset:4096
	v_cvt_pk_bf16_f32 v90, v105, v106
	ds_read_b64 v[104:105], v110 offset:4096
	ds_read_b64 v[106:107], v111 offset:4096
	s_waitcnt lgkmcnt(8)
	s_nop 1
	v_mfma_f32_16x16x32_bf16 v[64:67], v[80:83], v[88:91], v[64:67]
	v_mfma_f32_16x16x32_bf16 v[80:83], v[80:83], v[68:71], v[60:63]
	v_mfma_f32_16x16x32_bf16 v[60:63], v[84:87], v[72:75], v[64:67]
	v_mfma_f32_16x16x32_bf16 v[64:67], v[84:87], v[76:79], v[80:83]
	ds_read_b64 v[80:81], v0 offset:6144
	ds_read_b64 v[82:83], v3 offset:6144
	ds_read_b64 v[84:85], v110 offset:6144
	ds_read_b64 v[86:87], v111 offset:6144
	s_waitcnt lgkmcnt(8)
	v_mfma_f32_16x16x32_bf16 v[56:59], v[92:95], v[88:91], v[56:59]
	v_mfma_f32_16x16x32_bf16 v[92:95], v[92:95], v[68:71], v[52:55]
	v_mfma_f32_16x16x32_bf16 v[52:55], v[96:99], v[72:75], v[56:59]
	v_mfma_f32_16x16x32_bf16 v[56:59], v[96:99], v[76:79], v[92:95]
	ds_read_b64 v[92:93], v0 offset:8192
	ds_read_b64 v[94:95], v3 offset:8192
	ds_read_b64 v[96:97], v110 offset:8192
	ds_read_b64 v[98:99], v111 offset:8192
	s_waitcnt lgkmcnt(8)
	v_mfma_f32_16x16x32_bf16 v[48:51], v[100:103], v[88:91], v[48:51]
	v_mfma_f32_16x16x32_bf16 v[100:103], v[100:103], v[68:71], v[44:47]
	v_mfma_f32_16x16x32_bf16 v[44:47], v[104:107], v[72:75], v[48:51]
	v_mfma_f32_16x16x32_bf16 v[48:51], v[104:107], v[76:79], v[100:103]
	ds_read_b64 v[100:101], v0 offset:10240
	ds_read_b64 v[102:103], v3 offset:10240
	ds_read_b64 v[104:105], v110 offset:10240
	ds_read_b64 v[106:107], v111 offset:10240
	s_waitcnt lgkmcnt(8)
	v_mfma_f32_16x16x32_bf16 v[40:43], v[80:83], v[88:91], v[40:43]
	v_mfma_f32_16x16x32_bf16 v[80:83], v[80:83], v[68:71], v[36:39]
	v_mfma_f32_16x16x32_bf16 v[36:39], v[84:87], v[72:75], v[40:43]
	v_mfma_f32_16x16x32_bf16 v[40:43], v[84:87], v[76:79], v[80:83]
	ds_read_b64 v[80:81], v0 offset:12288
	ds_read_b64 v[82:83], v3 offset:12288
	ds_read_b64 v[84:85], v110 offset:12288
	ds_read_b64 v[86:87], v111 offset:12288
	s_waitcnt lgkmcnt(8)
	v_mfma_f32_16x16x32_bf16 v[32:35], v[92:95], v[88:91], v[32:35]
	v_mfma_f32_16x16x32_bf16 v[92:95], v[92:95], v[68:71], v[28:31]
	v_mfma_f32_16x16x32_bf16 v[28:31], v[96:99], v[72:75], v[32:35]
	v_mfma_f32_16x16x32_bf16 v[32:35], v[96:99], v[76:79], v[92:95]
	ds_read_b64 v[92:93], v0 offset:14336
	ds_read_b64 v[94:95], v3 offset:14336
	ds_read_b64 v[96:97], v110 offset:14336
	ds_read_b64 v[98:99], v111 offset:14336
	s_waitcnt lgkmcnt(8)
	v_mfma_f32_16x16x32_bf16 v[24:27], v[100:103], v[88:91], v[24:27]
	v_mfma_f32_16x16x32_bf16 v[100:103], v[100:103], v[68:71], v[16:19]
	v_mfma_f32_16x16x32_bf16 v[16:19], v[104:107], v[72:75], v[24:27]
	v_mfma_f32_16x16x32_bf16 v[100:103], v[104:107], v[76:79], v[100:103]
	s_waitcnt lgkmcnt(4)
	v_mfma_f32_16x16x32_bf16 v[20:23], v[80:83], v[88:91], v[20:23]
	v_mfma_f32_16x16x32_bf16 v[24:27], v[80:83], v[68:71], v[8:11]
	v_mfma_f32_16x16x32_bf16 v[8:11], v[84:87], v[72:75], v[20:23]
	v_mfma_f32_16x16x32_bf16 v[80:83], v[84:87], v[76:79], v[24:27]
	s_waitcnt lgkmcnt(0)
	v_mfma_f32_16x16x32_bf16 v[12:15], v[92:95], v[88:91], v[12:15]
	v_mfma_f32_16x16x32_bf16 v[4:7], v[92:95], v[68:71], v[4:7]
	v_mfma_f32_16x16x32_bf16 v[68:71], v[96:99], v[72:75], v[12:15]
	v_mfma_f32_16x16x32_bf16 v[72:75], v[96:99], v[76:79], v[4:7]
	ds_bpermute_b32 v0, v136, v108
	s_waitcnt lgkmcnt(0)
	v_add_f32_e32 v0, v108, v0
	ds_bpermute_b32 v3, v135, v0
	s_waitcnt lgkmcnt(0)
	v_add_f32_e32 v0, v0, v3
	ds_bpermute_b32 v3, v136, v109
	v_div_scale_f32 v4, s[6:7], v0, v0, 1.0
	v_rcp_f32_e32 v5, v4
	s_waitcnt lgkmcnt(0)
	v_add_f32_e32 v3, v109, v3
	ds_bpermute_b32 v117, v135, v3
	v_fma_f32 v6, -v4, v5, 1.0
	v_fmac_f32_e32 v5, v6, v5
	v_div_scale_f32 v6, vcc, 1.0, v0, 1.0
	v_mul_f32_e32 v7, v6, v5
	v_fma_f32 v12, -v4, v7, v6
	v_fmac_f32_e32 v7, v12, v5
	v_fma_f32 v4, -v4, v7, v6
	s_waitcnt lgkmcnt(0)
	v_pk_add_f32 v[2:3], v[116:117], v[2:3]
	v_div_fmas_f32 v4, v4, v5, v7
	v_div_fixup_f32 v0, v4, v0, 1.0
	v_div_scale_f32 v4, s[6:7], v3, v3, v2
	v_rcp_f32_e32 v5, v4
	v_readlane_b32 s6, v217, 30
	v_readlane_b32 s7, v217, 31
	v_fma_f32 v6, -v4, v5, 1.0
	v_fmac_f32_e32 v5, v6, v5
	v_div_scale_f32 v6, vcc, v2, v3, v2
	v_mul_f32_e32 v7, v6, v5
	v_fma_f32 v12, -v4, v7, v6
	v_fmac_f32_e32 v7, v12, v5
	v_fma_f32 v4, -v4, v7, v6
	v_div_fmas_f32 v4, v4, v5, v7
	v_div_fixup_f32 v2, v4, v3, v2
	v_pk_mul_f32 v[4:5], v[64:65], v[2:3] op_sel_hi:[1,0]
	v_pk_mul_f32 v[6:7], v[66:67], v[2:3] op_sel_hi:[1,0]
	v_pk_fma_f32 v[12:13], v[60:61], v[0:1], v[4:5] op_sel_hi:[1,0,1] neg_lo:[0,0,1] neg_hi:[0,0,1]
	v_pk_fma_f32 v[6:7], v[62:63], v[0:1], v[6:7] op_sel_hi:[1,0,1] neg_lo:[0,0,1] neg_hi:[0,0,1]
	v_mul_f32_e32 v3, v13, v13
	v_fmac_f32_e32 v3, v12, v12
	v_fmac_f32_e32 v3, v6, v6
	v_fmac_f32_e32 v3, v7, v7
	v_pk_mul_f32 v[4:5], v[56:57], v[2:3] op_sel_hi:[1,0]
	v_pk_mul_f32 v[14:15], v[58:59], v[2:3] op_sel_hi:[1,0]
	v_pk_fma_f32 v[22:23], v[52:53], v[0:1], v[4:5] op_sel_hi:[1,0,1] neg_lo:[0,0,1] neg_hi:[0,0,1]
	v_pk_fma_f32 v[14:15], v[54:55], v[0:1], v[14:15] op_sel_hi:[1,0,1] neg_lo:[0,0,1] neg_hi:[0,0,1]
	v_mul_f32_e32 v4, v23, v23
	v_fmac_f32_e32 v4, v22, v22
	v_fmac_f32_e32 v4, v14, v14
	v_fmac_f32_e32 v4, v15, v15
	v_add_f32_e32 v3, v3, v4
	v_pk_mul_f32 v[4:5], v[48:49], v[2:3] op_sel_hi:[1,0]
	v_pk_mul_f32 v[20:21], v[50:51], v[2:3] op_sel_hi:[1,0]
	v_pk_fma_f32 v[44:45], v[44:45], v[0:1], v[4:5] op_sel_hi:[1,0,1] neg_lo:[0,0,1] neg_hi:[0,0,1]
	v_pk_mul_f32 v[4:5], v[40:41], v[2:3] op_sel_hi:[1,0]
	v_pk_fma_f32 v[26:27], v[46:47], v[0:1], v[20:21] op_sel_hi:[1,0,1] neg_lo:[0,0,1] neg_hi:[0,0,1]
	v_pk_fma_f32 v[24:25], v[36:37], v[0:1], v[4:5] op_sel_hi:[1,0,1] neg_lo:[0,0,1] neg_hi:[0,0,1]
	v_pk_mul_f32 v[20:21], v[42:43], v[2:3] op_sel_hi:[1,0]
	v_mov_b32_e32 v36, v25
	v_mov_b32_e32 v37, v45
	v_pk_fma_f32 v[20:21], v[38:39], v[0:1], v[20:21] op_sel_hi:[1,0,1] neg_lo:[0,0,1] neg_hi:[0,0,1]
	v_mov_b32_e32 v4, v24
	v_mov_b32_e32 v5, v44
	v_pk_mul_f32 v[36:37], v[36:37], v[36:37]
	s_nop 0
	v_pk_fma_f32 v[4:5], v[4:5], v[4:5], v[36:37]
	v_mov_b32_e32 v36, v20
	v_mov_b32_e32 v37, v26
	v_pk_fma_f32 v[4:5], v[36:37], v[36:37], v[4:5]
	v_mov_b32_e32 v36, v21
	v_mov_b32_e32 v37, v27
	v_pk_fma_f32 v[4:5], v[36:37], v[36:37], v[4:5]
	v_lshlrev_b32_e32 v37, 4, v134
	v_add_f32_e32 v3, v5, v3
	v_add_f32_e32 v3, v4, v3
	v_pk_mul_f32 v[4:5], v[32:33], v[2:3] op_sel_hi:[1,0]
	v_pk_mul_f32 v[32:33], v[34:35], v[2:3] op_sel_hi:[1,0]
	v_pk_fma_f32 v[34:35], v[28:29], v[0:1], v[4:5] op_sel_hi:[1,0,1] neg_lo:[0,0,1] neg_hi:[0,0,1]
	v_pk_mul_f32 v[4:5], v[100:101], v[2:3] op_sel_hi:[1,0]
	v_pk_mul_f32 v[28:29], v[102:103], v[2:3] op_sel_hi:[1,0]
	v_pk_fma_f32 v[16:17], v[16:17], v[0:1], v[4:5] op_sel_hi:[1,0,1] neg_lo:[0,0,1] neg_hi:[0,0,1]
	v_pk_fma_f32 v[18:19], v[18:19], v[0:1], v[28:29] op_sel_hi:[1,0,1] neg_lo:[0,0,1] neg_hi:[0,0,1]
	v_mov_b32_e32 v28, v17
	v_mov_b32_e32 v29, v35
	v_pk_fma_f32 v[30:31], v[30:31], v[0:1], v[32:33] op_sel_hi:[1,0,1] neg_lo:[0,0,1] neg_hi:[0,0,1]
	v_mov_b32_e32 v4, v16
	v_mov_b32_e32 v5, v34
	v_pk_mul_f32 v[28:29], v[28:29], v[28:29]
	s_nop 0
	v_pk_fma_f32 v[4:5], v[4:5], v[4:5], v[28:29]
	v_mov_b32_e32 v28, v18
	v_mov_b32_e32 v29, v30
	v_pk_fma_f32 v[4:5], v[28:29], v[28:29], v[4:5]
	v_mov_b32_e32 v28, v19
	v_mov_b32_e32 v29, v31
	v_pk_fma_f32 v[4:5], v[28:29], v[28:29], v[4:5]
	s_nop 0
	v_add_f32_e32 v3, v5, v3
	v_add_f32_e32 v36, v4, v3
	v_pk_mul_f32 v[4:5], v[80:81], v[2:3] op_sel_hi:[1,0]
	v_pk_mul_f32 v[28:29], v[82:83], v[2:3] op_sel_hi:[1,0]
	v_pk_fma_f32 v[32:33], v[8:9], v[0:1], v[4:5] op_sel_hi:[1,0,1] neg_lo:[0,0,1] neg_hi:[0,0,1]
	v_pk_mul_f32 v[4:5], v[72:73], v[2:3] op_sel_hi:[1,0]
	v_pk_fma_f32 v[28:29], v[10:11], v[0:1], v[28:29] op_sel_hi:[1,0,1] neg_lo:[0,0,1] neg_hi:[0,0,1]
	v_pk_fma_f32 v[10:11], v[68:69], v[0:1], v[4:5] op_sel_hi:[1,0,1] neg_lo:[0,0,1] neg_hi:[0,0,1]
	v_pk_mul_f32 v[2:3], v[74:75], v[2:3] op_sel_hi:[1,0]
	v_mov_b32_e32 v4, v11
	v_mov_b32_e32 v5, v33
	v_pk_fma_f32 v[8:9], v[70:71], v[0:1], v[2:3] op_sel_hi:[1,0,1] neg_lo:[0,0,1] neg_hi:[0,0,1]
	v_mov_b32_e32 v2, v10
	v_mov_b32_e32 v3, v32
	v_pk_mul_f32 v[4:5], v[4:5], v[4:5]
	s_nop 0
	v_pk_fma_f32 v[2:3], v[2:3], v[2:3], v[4:5]
	v_mov_b32_e32 v4, v8
	v_mov_b32_e32 v5, v28
	v_pk_fma_f32 v[2:3], v[4:5], v[4:5], v[2:3]
	v_mov_b32_e32 v4, v9
	v_mov_b32_e32 v5, v29
	v_pk_fma_f32 v[2:3], v[4:5], v[4:5], v[2:3]
	s_nop 0
	v_add_f32_e32 v0, v3, v36
	v_add_f32_e32 v0, v2, v0
	ds_bpermute_b32 v2, v136, v0
	s_waitcnt lgkmcnt(0)
	v_add_f32_e32 v0, v0, v2
	ds_bpermute_b32 v2, v135, v0
	s_waitcnt lgkmcnt(0)
	v_add_f32_e32 v0, v0, v2
	v_fmamk_f32 v0, v0, 0x3c000000, v144
	v_rsq_f32_e32 v0, v0
	v_lshl_add_u64 v[2:3], v[120:121], 1, s[6:7]
	v_mul_f32_e32 v36, v119, v0
	v_lshlrev_b32_e32 v0, 1, v118
	v_lshl_add_u64 v[2:3], v[2:3], 0, v[0:1]
	v_lshlrev_b32_e32 v0, 3, v134
	v_lshl_add_u64 v[38:39], v[2:3], 0, v[0:1]
	global_load_dwordx4 v[2:5], v37, s[92:93]
	v_pk_mul_f32 v[12:13], v[12:13], v[36:37] op_sel_hi:[1,0]
	v_pk_mul_f32 v[6:7], v[6:7], v[36:37] op_sel_hi:[1,0]
	v_pk_mul_f32 v[8:9], v[8:9], v[36:37] op_sel_hi:[1,0]
	s_waitcnt vmcnt(0)
	v_pk_mul_f32 v[4:5], v[4:5], v[6:7]
	v_pk_mul_f32 v[2:3], v[2:3], v[12:13]
	v_pk_mul_f32 v[6:7], v[22:23], v[36:37] op_sel_hi:[1,0]
	v_cvt_pk_bf16_f32 v2, v2, v3
	v_cvt_pk_bf16_f32 v3, v4, v5
	global_store_dwordx2 v[38:39], v[2:3], off
	global_load_dwordx4 v[2:5], v37, s[92:93] offset:64
	v_pk_mul_f32 v[12:13], v[14:15], v[36:37] op_sel_hi:[1,0]
	s_waitcnt vmcnt(0)
	v_pk_mul_f32 v[2:3], v[2:3], v[6:7]
	v_pk_mul_f32 v[4:5], v[4:5], v[12:13]
	v_cvt_pk_bf16_f32 v2, v2, v3
	v_cvt_pk_bf16_f32 v3, v4, v5
	global_store_dwordx2 v[38:39], v[2:3], off offset:32
	global_load_dwordx4 v[2:5], v37, s[92:93] offset:128
	v_pk_mul_f32 v[6:7], v[44:45], v[36:37] op_sel_hi:[1,0]
	v_pk_mul_f32 v[12:13], v[26:27], v[36:37] op_sel_hi:[1,0]
	s_waitcnt vmcnt(0)
	v_pk_mul_f32 v[2:3], v[2:3], v[6:7]
	v_pk_mul_f32 v[4:5], v[4:5], v[12:13]
	v_cvt_pk_bf16_f32 v2, v2, v3
	v_cvt_pk_bf16_f32 v3, v4, v5
	global_store_dwordx2 v[38:39], v[2:3], off offset:64
	global_load_dwordx4 v[2:5], v37, s[92:93] offset:192
	v_pk_mul_f32 v[6:7], v[24:25], v[36:37] op_sel_hi:[1,0]
	v_pk_mul_f32 v[12:13], v[20:21], v[36:37] op_sel_hi:[1,0]
	s_waitcnt vmcnt(0)
	v_pk_mul_f32 v[2:3], v[2:3], v[6:7]
	v_pk_mul_f32 v[4:5], v[4:5], v[12:13]
	v_cvt_pk_bf16_f32 v2, v2, v3
	v_cvt_pk_bf16_f32 v3, v4, v5
	global_store_dwordx2 v[38:39], v[2:3], off offset:96
	global_load_dwordx4 v[2:5], v37, s[92:93] offset:256
	v_pk_mul_f32 v[6:7], v[34:35], v[36:37] op_sel_hi:[1,0]
	v_pk_mul_f32 v[12:13], v[30:31], v[36:37] op_sel_hi:[1,0]
	s_waitcnt vmcnt(0)
	v_pk_mul_f32 v[2:3], v[2:3], v[6:7]
	v_pk_mul_f32 v[4:5], v[4:5], v[12:13]
	v_cvt_pk_bf16_f32 v2, v2, v3
	v_cvt_pk_bf16_f32 v3, v4, v5
	global_store_dwordx2 v[38:39], v[2:3], off offset:128
	global_load_dwordx4 v[2:5], v37, s[92:93] offset:320
	v_pk_mul_f32 v[6:7], v[16:17], v[36:37] op_sel_hi:[1,0]
	v_pk_mul_f32 v[12:13], v[18:19], v[36:37] op_sel_hi:[1,0]
	s_waitcnt vmcnt(0)
	v_pk_mul_f32 v[2:3], v[2:3], v[6:7]
	v_pk_mul_f32 v[4:5], v[4:5], v[12:13]
	v_cvt_pk_bf16_f32 v2, v2, v3
	v_cvt_pk_bf16_f32 v3, v4, v5
	global_store_dwordx2 v[38:39], v[2:3], off offset:160
	global_load_dwordx4 v[2:5], v37, s[92:93] offset:384
	v_pk_mul_f32 v[6:7], v[32:33], v[36:37] op_sel_hi:[1,0]
	v_pk_mul_f32 v[12:13], v[28:29], v[36:37] op_sel_hi:[1,0]
	s_waitcnt vmcnt(0)
	v_pk_mul_f32 v[2:3], v[2:3], v[6:7]
	v_pk_mul_f32 v[4:5], v[4:5], v[12:13]
	v_cvt_pk_bf16_f32 v2, v2, v3
	v_cvt_pk_bf16_f32 v3, v4, v5
	global_store_dwordx2 v[38:39], v[2:3], off offset:192
	global_load_dwordx4 v[2:5], v37, s[92:93] offset:448
	v_pk_mul_f32 v[6:7], v[10:11], v[36:37] op_sel_hi:[1,0]
	s_waitcnt vmcnt(0)
	v_pk_mul_f32 v[4:5], v[4:5], v[8:9]
	v_pk_mul_f32 v[2:3], v[2:3], v[6:7]
	s_nop 0
	v_cvt_pk_bf16_f32 v2, v2, v3
	v_cvt_pk_bf16_f32 v3, v4, v5
	global_store_dwordx2 v[38:39], v[2:3], off offset:224

.LBB0_152:
	s_andn2_saveexec_b64 s[4:5], s[40:41]
	s_cbranch_execz .LBB0_115
	v_mov_b32_e32 v24, v142
	v_readlane_b32 s8, v217, 15
	v_and_b32_e32 v4, 63, v24
	v_lshlrev_b32_e32 v4, 2, v4
	global_load_dword v22, v4, s[42:43]
	global_load_dword v23, v4, s[42:43] offset:256
	global_load_dword v25, v4, s[42:43] offset:512
	global_load_dword v26, v4, s[42:43] offset:768
	v_cmp_lt_i32_e32 vcc, v149, v148
	v_readlane_b32 s9, v217, 16
	v_lshrrev_b32_e32 v27, 3, v0
	v_cndmask_b32_e32 v10, v147, v149, vcc
	v_cmp_lt_i32_e32 vcc, v150, v148
	v_lshlrev_b32_e32 v8, 7, v2
	v_mov_b64_e32 v[4:5], s[8:9]
	v_and_b32_e32 v9, 0xf8, v2
	v_readlane_b32 s8, v217, 11
	v_cndmask_b32_e32 v11, v147, v150, vcc
	v_cmp_lt_i32_e32 vcc, v151, v148
	v_readlane_b32 s9, v217, 12
	v_lshlrev_b32_e32 v14, 10, v27
	v_cndmask_b32_e32 v12, v147, v151, vcc
	v_cmp_lt_i32_e32 vcc, v152, v148
	v_and_b32_e32 v15, 0x380, v8
	v_or_b32_e32 v8, s19, v27
	v_add3_u32 v28, v9, s94, v3
	v_and_b32_e32 v31, 15, v24
	v_ashrrev_i32_e32 v9, 2, v24
	s_mov_b32 s12, 0x280000
	v_mov_b64_e32 v[6:7], s[8:9]
	v_cndmask_b32_e32 v13, v147, v152, vcc
	v_lshlrev_b32_e32 v136, 2, v11
	v_lshlrev_b32_e32 v29, 2, v12
	v_mad_i64_i32 v[4:5], s[8:9], v8, s12, v[4:5]
	v_ashrrev_i32_e32 v8, 4, v24
	v_add_u32_e32 v32, 0x200, v24
	v_and_b32_e32 v11, -16, v9
	v_or3_b32 v12, v15, v14, v31
	v_lshlrev_b32_e32 v135, 2, v10
	v_lshlrev_b32_e32 v30, 2, v13
	v_xor_b32_e32 v13, v8, v24
	v_ashrrev_i32_e32 v9, 31, v8
	v_ashrrev_i32_e32 v10, 4, v32
	v_add3_u32 v12, v11, v12, s88
	v_lshlrev_b64 v[14:15], 11, v[8:9]
	v_lshlrev_b32_e32 v9, 4, v13
	v_xor_b32_e32 v20, v10, v24
	v_ashrrev_i32_e32 v11, 31, v10
	v_ashrrev_i32_e32 v13, 31, v12
	v_readlane_b32 s10, v217, 45
	v_lshlrev_b64 v[18:19], 11, v[10:11]
	v_lshlrev_b32_e32 v11, 4, v20
	v_lshlrev_b64 v[20:21], 11, v[12:13]
	v_readlane_b32 s11, v217, 46
	v_lshlrev_b32_e32 v0, 8, v3
	v_lshl_add_u64 v[4:5], v[4:5], 0, v[0:1]
	v_lshl_add_u64 v[20:21], s[10:11], 0, v[20:21]
	v_lshl_add_u64 v[20:21], v[20:21], 0, v[0:1]
	v_and_b32_e32 v0, 48, v24
	v_lshl_add_u64 v[20:21], v[20:21], 0, v[0:1]
	v_and_b32_e32 v0, 0xf0, v9
	global_load_dwordx4 v[76:79], v[20:21], off
	global_load_dwordx4 v[80:83], v[20:21], off offset:64
	global_load_dwordx4 v[68:71], v[20:21], off offset:128
	global_load_dwordx4 v[72:75], v[20:21], off offset:192
	v_lshrrev_b32_e32 v33, 4, v24
	v_xor_b32_e32 v16, v33, v24
	v_lshlrev_b32_e32 v36, 4, v16
	v_lshl_add_u64 v[16:17], v[4:5], 0, v[14:15]
	v_lshl_add_u64 v[16:17], v[16:17], 0, v[0:1]
	v_and_b32_e32 v0, 0xf0, v11
	v_lshlrev_b32_e32 v162, 4, v24
	s_mov_b32 s13, 0x50000
	v_add_u32_e32 v34, 0, v162
	v_lshlrev_b32_e32 v164, 4, v32
	v_mad_i64_i32 v[6:7], s[8:9], v28, s13, v[6:7]
	v_readfirstlane_b32 s7, v34
	v_add_u32_e32 v35, 0, v164
	v_lshl_add_u64 v[4:5], v[4:5], 0, v[18:19]
	v_readfirstlane_b32 s8, v35
	s_mov_b32 m0, s7
	v_lshl_add_u64 v[4:5], v[4:5], 0, v[0:1]
	v_and_b32_e32 v0, 0x70, v36
	s_barrier
	s_waitcnt vmcnt(6)
	v_mul_f32_e32 v9, v22, v23
	ds_bpermute_b32 v9, v135, v9
	s_waitcnt vmcnt(4)
	v_mul_f32_e32 v20, v25, v26
	ds_bpermute_b32 v20, v135, v20
	global_load_lds_dwordx4 v[16:17], off
	s_waitcnt lgkmcnt(0)
	v_fmac_f32_e32 v9, v22, v23
	ds_bpermute_b32 v11, v136, v9
	v_fmac_f32_e32 v20, v25, v26
	ds_bpermute_b32 v21, v136, v20
	s_mov_b32 m0, s8
	s_movk_i32 s10, 0xa00
	s_waitcnt lgkmcnt(0)
	v_add_f32_e32 v9, v9, v11
	global_load_lds_dwordx4 v[4:5], off
	v_add_f32_e32 v11, v20, v21
	ds_bpermute_b32 v20, v29, v9
	ds_bpermute_b32 v21, v29, v11
	v_ashrrev_i32_e32 v29, 3, v24
	v_lshl_add_u64 v[16:17], v[16:17], 0, s[46:47]
	v_lshl_add_u64 v[4:5], v[4:5], 0, s[46:47]
	s_waitcnt lgkmcnt(0)
	v_add_f32_e32 v9, v9, v20
	v_add_f32_e32 v11, v11, v21
	ds_bpermute_b32 v25, v30, v9
	ds_bpermute_b32 v26, v30, v11
	v_add_u32_e32 v30, 0x4000, v34
	v_lshl_add_u64 v[20:21], v[6:7], 0, v[0:1]
	v_readfirstlane_b32 s7, v30
	v_mad_i64_i32 v[22:23], s[8:9], v29, s10, v[20:21]
	s_mov_b32 m0, s7
	v_bfe_u32 v134, v24, 4, 2
	global_load_lds_dwordx4 v[22:23], off
	v_add_u32_e32 v23, 0x4000, v35
	v_ashrrev_i32_e32 v22, 3, v32
	v_readfirstlane_b32 s7, v23
	v_mad_i64_i32 v[20:21], s[8:9], v22, s10, v[20:21]
	s_mov_b32 m0, s7
	v_lshlrev_b32_e32 v118, 7, v3
	global_load_lds_dwordx4 v[20:21], off
	v_add_u32_e32 v20, 0x8000, v34
	v_lshl_add_u32 v3, v31, 8, 0
	v_readfirstlane_b32 s7, v20
	s_mov_b32 m0, s7
	v_cmp_lt_i32_e32 vcc, v153, v148
	global_load_lds_dwordx4 v[16:17], off
	v_add_u32_e32 v16, 0x8000, v35
	s_waitcnt lgkmcnt(0)
	v_add_f32_e32 v165, v9, v25
	v_readfirstlane_b32 s7, v16
	s_mov_b32 m0, s7
	v_add_u32_e32 v16, 0xc000, v34
	global_load_lds_dwordx4 v[4:5], off
	v_mad_i64_i32 v[4:5], s[8:9], v29, s10, v[6:7]
	v_lshl_add_u64 v[4:5], v[4:5], 0, v[0:1]
	v_readfirstlane_b32 s7, v16
	v_lshl_add_u64 v[4:5], v[4:5], 0, s[30:31]
	s_mov_b32 m0, s7
	v_add_f32_e32 v169, v11, v26
	global_load_lds_dwordx4 v[4:5], off
	v_mad_i64_i32 v[4:5], s[8:9], v22, s10, v[6:7]
	v_lshl_add_u64 v[4:5], v[4:5], 0, v[0:1]
	v_add_u32_e32 v0, 0xc000, v35
	v_lshl_add_u64 v[4:5], v[4:5], 0, s[30:31]
	v_readfirstlane_b32 s7, v0
	s_mov_b32 m0, s7
	v_cndmask_b32_e32 v0, v147, v153, vcc
	global_load_lds_dwordx4 v[4:5], off
	v_bitop3_b32 v4, v134, v24, 15 bitop3:0x78
	v_lshl_add_u32 v166, v4, 4, v3
	v_bitop3_b32 v4, v134, v31, 4 bitop3:0x36
	v_lshl_add_u32 v167, v4, 4, v3
	v_bitop3_b32 v4, v134, v31, 8 bitop3:0x36
	v_lshlrev_b32_e32 v0, 2, v0
	v_lshl_add_u32 v168, v4, 4, v3
	v_bitop3_b32 v4, v134, v31, 12 bitop3:0x36
	s_add_i32 s8, 0, 0x4000
	ds_bpermute_b32 v170, v0, v165
	ds_bpermute_b32 v172, v0, v169
	v_lshrrev_b32_e32 v0, 1, v24
	v_lshl_add_u32 v171, v4, 4, v3
	v_lshl_add_u32 v4, v31, 7, s8
	v_bfe_u32 v5, v24, 5, 1
	v_bfe_u32 v3, v24, 1, 3
	v_and_or_b32 v4, v0, 8, v4
	v_bitop3_b32 v0, v5, v0, 7 bitop3:0x78
	v_lshl_add_u32 v117, v0, 4, v4
	v_bitop3_b32 v0, v5, v3, 2 bitop3:0x36
	v_lshl_add_u32 v137, v0, 4, v4
	v_bitop3_b32 v0, v5, v3, 4 bitop3:0x36
	v_lshl_add_u32 v138, v0, 4, v4
	v_bitop3_b32 v0, v5, v3, 6 bitop3:0x36
	v_lshl_add_u32 v139, v0, 4, v4
	v_mad_i64_i32 v[4:5], s[8:9], v28, s13, v[130:131]
	v_bitop3_b32 v0, v33, 7, v24 bitop3:0x48
	v_mad_i64_i32 v[122:123], s[8:9], v22, s10, v[4:5]
	v_lshlrev_b32_e32 v0, 4, v0
	v_mad_i64_i32 v[124:125], s[8:9], v29, s10, v[4:5]
	v_or_b32_e32 v122, v122, v0
	v_or_b32_e32 v124, v124, v0
	v_add_u32_e32 v0, s19, v27
	v_mad_i64_i32 v[4:5], s[8:9], v0, s12, v[132:133]
	v_lshl_add_u64 v[6:7], v[4:5], 0, v[14:15]
	v_and_b32_e32 v0, 0xffffff00, v2
	v_lshl_add_u64 v[126:127], v[6:7], 0, v[0:1]
	v_bitop3_b32 v2, v8, 15, v24 bitop3:0x48
	v_lshl_or_b32 v126, v2, 4, v126
	v_lshl_add_u64 v[2:3], v[4:5], 0, v[18:19]
	v_lshl_add_u64 v[128:129], v[2:3], 0, v[0:1]
	v_bitop3_b32 v0, v10, 15, v24 bitop3:0x48
	v_mov_b32_e32 v2, v1
	v_mov_b32_e32 v3, v1
	v_lshlrev_b64 v[120:121], 10, v[12:13]
	v_lshl_or_b32 v128, v0, 4, v128
	v_mov_b32_e32 v0, v1
	v_mov_b64_e32 v[6:7], v[2:3]
	v_mov_b64_e32 v[10:11], v[2:3]
	v_mov_b64_e32 v[18:19], v[2:3]
	v_mov_b64_e32 v[30:31], v[2:3]
	v_mov_b64_e32 v[38:39], v[2:3]
	v_mov_b64_e32 v[46:47], v[2:3]
	v_mov_b64_e32 v[54:55], v[2:3]
	v_mov_b64_e32 v[62:63], v[2:3]
	v_mov_b64_e32 v[66:67], v[2:3]
	v_mov_b64_e32 v[58:59], v[2:3]
	v_mov_b64_e32 v[50:51], v[2:3]
	v_mov_b64_e32 v[42:43], v[2:3]
	v_mov_b64_e32 v[34:35], v[2:3]
	v_mov_b64_e32 v[26:27], v[2:3]
	v_mov_b64_e32 v[22:23], v[2:3]
	v_mov_b64_e32 v[14:15], v[2:3]
	s_mov_b32 s6, 2
	s_mov_b32 s7, 0
	v_mov_b32_e32 v140, 0
	v_mov_b32_e32 v161, 0xf149f2ca
	v_mov_b64_e32 v[4:5], v[0:1]
	v_mov_b64_e32 v[8:9], v[0:1]
	v_mov_b64_e32 v[16:17], v[0:1]
	v_mov_b64_e32 v[28:29], v[0:1]
	v_mov_b64_e32 v[36:37], v[0:1]
	v_mov_b64_e32 v[44:45], v[0:1]
	v_mov_b64_e32 v[52:53], v[0:1]
	v_mov_b64_e32 v[60:61], v[0:1]
	v_mov_b32_e32 v163, 0xf149f2ca
	v_mov_b32_e32 v141, 0
	v_mov_b64_e32 v[64:65], v[0:1]
	v_mov_b64_e32 v[56:57], v[0:1]
	v_mov_b64_e32 v[48:49], v[0:1]
	v_mov_b64_e32 v[40:41], v[0:1]
	v_mov_b64_e32 v[32:33], v[0:1]
	v_mov_b64_e32 v[24:25], v[0:1]
	v_mov_b64_e32 v[20:21], v[0:1]
	v_mov_b64_e32 v[12:13], v[0:1]
	s_mov_b32 s8, 0
	s_waitcnt vmcnt(0)
	v_readfirstlane_b32 s10, v142
	s_bitcmp1_b32 s10, 8
	s_cbranch_scc1 .Lat_b_loop
	s_branch .LBB0_155
.LBB0_154:
	v_sub_f32_e32 v0, v112, v163
	v_exp_f32_e32 v0, v0
	v_sub_f32_e32 v2, v113, v163
	v_exp_f32_e32 v2, v2
	v_sub_f32_e32 v3, v114, v163
	v_exp_f32_e32 v3, v3
	v_sub_f32_e32 v112, v115, v163
	v_exp_f32_e32 v112, v112
	v_sub_f32_e32 v108, v108, v163
	v_add_f32_e32 v113, 0, v0
	v_exp_f32_e32 v108, v108
	v_sub_f32_e32 v109, v109, v163
	v_add_f32_e32 v113, v2, v113
	v_exp_f32_e32 v109, v109
	v_sub_f32_e32 v110, v110, v163
	v_add_f32_e32 v113, v3, v113
	v_exp_f32_e32 v110, v110
	v_sub_f32_e32 v111, v111, v163
	v_add_f32_e32 v113, v112, v113
	v_exp_f32_e32 v111, v111
	v_sub_f32_e32 v104, v104, v163
	v_add_f32_e32 v113, v108, v113
	v_exp_f32_e32 v104, v104
	v_sub_f32_e32 v105, v105, v163
	v_add_f32_e32 v113, v109, v113
	v_exp_f32_e32 v105, v105
	v_sub_f32_e32 v106, v106, v163
	v_add_f32_e32 v113, v110, v113
	v_exp_f32_e32 v106, v106
	v_sub_f32_e32 v107, v107, v163
	v_add_f32_e32 v113, v111, v113
	v_exp_f32_e32 v107, v107
	v_sub_f32_e32 v100, v100, v163
	v_add_f32_e32 v113, v104, v113
	v_exp_f32_e32 v114, v100
	v_sub_f32_e32 v100, v101, v163
	v_add_f32_e32 v113, v105, v113
	v_exp_f32_e32 v115, v100
	v_sub_f32_e32 v100, v102, v163
	v_add_f32_e32 v113, v106, v113
	v_exp_f32_e32 v173, v100
	v_sub_f32_e32 v100, v103, v163
	v_add_f32_e32 v113, v107, v113
	v_exp_f32_e32 v174, v100
	v_add_f32_e32 v100, v114, v113
	v_add_f32_e32 v100, v115, v100
	v_add_f32_e32 v100, v173, v100
	v_add_f32_e32 v100, v174, v100
	v_add_f32_e32 v141, v141, v100
	v_cvt_pk_bf16_f32 v100, v0, v2
	v_sub_f32_e32 v0, v96, v161
	v_exp_f32_e32 v0, v0
	v_sub_f32_e32 v2, v97, v161
	v_cvt_pk_bf16_f32 v101, v3, v112
	v_exp_f32_e32 v2, v2
	v_sub_f32_e32 v3, v98, v161
	v_exp_f32_e32 v3, v3
	v_sub_f32_e32 v96, v99, v161
	v_exp_f32_e32 v96, v96
	v_sub_f32_e32 v92, v92, v161
	v_add_f32_e32 v97, 0, v0
	v_exp_f32_e32 v92, v92
	v_sub_f32_e32 v93, v93, v161
	v_add_f32_e32 v97, v2, v97
	v_exp_f32_e32 v93, v93
	v_sub_f32_e32 v94, v94, v161
	v_add_f32_e32 v97, v3, v97
	v_exp_f32_e32 v94, v94
	v_sub_f32_e32 v95, v95, v161
	v_add_f32_e32 v97, v96, v97
	v_exp_f32_e32 v95, v95
	v_sub_f32_e32 v88, v88, v161
	v_add_f32_e32 v97, v92, v97
	v_exp_f32_e32 v88, v88
	v_sub_f32_e32 v89, v89, v161
	v_add_f32_e32 v97, v93, v97
	v_exp_f32_e32 v89, v89
	v_sub_f32_e32 v90, v90, v161
	v_add_f32_e32 v97, v94, v97
	v_exp_f32_e32 v90, v90
	v_sub_f32_e32 v91, v91, v161
	v_add_f32_e32 v97, v95, v97
	v_exp_f32_e32 v91, v91
	v_sub_f32_e32 v84, v84, v161
	v_add_f32_e32 v97, v88, v97
	v_exp_f32_e32 v98, v84
	v_sub_f32_e32 v84, v85, v161
	v_add_f32_e32 v97, v89, v97
	v_exp_f32_e32 v99, v84
	v_sub_f32_e32 v84, v86, v161
	v_cvt_pk_bf16_f32 v102, v108, v109
	v_add_f32_e32 v97, v90, v97
	v_exp_f32_e32 v108, v84
	v_sub_f32_e32 v84, v87, v161
	v_add_f32_e32 v97, v91, v97
	v_exp_f32_e32 v109, v84
	v_add_f32_e32 v84, v98, v97
	v_add_f32_e32 v84, v99, v84
	v_add_f32_e32 v84, v108, v84
	v_add_f32_e32 v84, v109, v84
	v_add_f32_e32 v140, v140, v84
	v_cvt_pk_bf16_f32 v84, v0, v2
	v_cvt_pk_bf16_f32 v86, v92, v93
	v_add_u32_e32 v0, s9, v117
	ds_read_b64 v[92:93], v0 offset:0
	v_cvt_pk_bf16_f32 v87, v94, v95
	v_add_u32_e32 v2, s9, v137
	ds_read_b64 v[94:95], v2 offset:0
	v_cvt_pk_bf16_f32 v85, v3, v96
	v_add_u32_e32 v3, s9, v138
	ds_read_b64 v[96:97], v3 offset:0
	v_cvt_pk_bf16_f32 v104, v104, v105
	v_cvt_pk_bf16_f32 v105, v106, v107
	v_cvt_pk_bf16_f32 v107, v173, v174
	v_cvt_pk_bf16_f32 v88, v88, v89
	v_cvt_pk_bf16_f32 v89, v90, v91
	v_cvt_pk_bf16_f32 v90, v98, v99
	v_add_u32_e32 v173, s9, v139
	ds_read_b64 v[98:99], v173 offset:0
	v_cvt_pk_bf16_f32 v91, v108, v109
	ds_read_b64 v[108:109], v0 offset:2048
	v_cvt_pk_bf16_f32 v103, v110, v111
	ds_read_b64 v[110:111], v2 offset:2048
	ds_read_b64 v[112:113], v3 offset:2048
	v_cvt_pk_bf16_f32 v106, v114, v115
	ds_read_b64 v[114:115], v173 offset:2048
	ds_read_b64 v[174:175], v0 offset:4096
	ds_read_b64 v[176:177], v2 offset:4096
	ds_read_b64 v[178:179], v3 offset:4096
	s_add_i32 s10, s7, 1
	ds_read_b64 v[180:181], v173 offset:4096
	s_cmp_lg_u32 s7, 3
	s_cselect_b32 s7, s10, 0
	s_add_i32 s8, s8, 1
	s_add_i32 s10, s6, 1
	s_waitcnt lgkmcnt(8)
	v_mfma_f32_16x16x32_bf16 v[64:67], v[92:95], v[100:103], v[64:67]
	v_mfma_f32_16x16x32_bf16 v[60:63], v[92:95], v[84:87], v[60:63]
	v_mfma_f32_16x16x32_bf16 v[64:67], v[96:99], v[104:107], v[64:67]
	v_mfma_f32_16x16x32_bf16 v[60:63], v[96:99], v[88:91], v[60:63]
	ds_read_b64 v[92:93], v0 offset:6144
	ds_read_b64 v[94:95], v2 offset:6144
	ds_read_b64 v[96:97], v3 offset:6144
	ds_read_b64 v[98:99], v173 offset:6144
	s_waitcnt lgkmcnt(8)
	v_mfma_f32_16x16x32_bf16 v[56:59], v[108:111], v[100:103], v[56:59]
	v_mfma_f32_16x16x32_bf16 v[52:55], v[108:111], v[84:87], v[52:55]
	v_mfma_f32_16x16x32_bf16 v[56:59], v[112:115], v[104:107], v[56:59]
	v_mfma_f32_16x16x32_bf16 v[52:55], v[112:115], v[88:91], v[52:55]
	ds_read_b64 v[108:109], v0 offset:8192
	ds_read_b64 v[110:111], v2 offset:8192
	ds_read_b64 v[112:113], v3 offset:8192
	ds_read_b64 v[114:115], v173 offset:8192
	s_waitcnt lgkmcnt(8)
	v_mfma_f32_16x16x32_bf16 v[48:51], v[174:177], v[100:103], v[48:51]
	v_mfma_f32_16x16x32_bf16 v[44:47], v[174:177], v[84:87], v[44:47]
	v_mfma_f32_16x16x32_bf16 v[48:51], v[178:181], v[104:107], v[48:51]
	v_mfma_f32_16x16x32_bf16 v[44:47], v[178:181], v[88:91], v[44:47]
	ds_read_b64 v[174:175], v0 offset:10240
	ds_read_b64 v[176:177], v2 offset:10240
	ds_read_b64 v[178:179], v3 offset:10240
	ds_read_b64 v[180:181], v173 offset:10240
	s_waitcnt lgkmcnt(8)
	v_mfma_f32_16x16x32_bf16 v[40:43], v[92:95], v[100:103], v[40:43]
	v_mfma_f32_16x16x32_bf16 v[36:39], v[92:95], v[84:87], v[36:39]
	v_mfma_f32_16x16x32_bf16 v[40:43], v[96:99], v[104:107], v[40:43]
	v_mfma_f32_16x16x32_bf16 v[36:39], v[96:99], v[88:91], v[36:39]
	ds_read_b64 v[92:93], v0 offset:12288
	ds_read_b64 v[94:95], v2 offset:12288
	ds_read_b64 v[96:97], v3 offset:12288
	ds_read_b64 v[98:99], v173 offset:12288
	s_waitcnt lgkmcnt(8)
	v_mfma_f32_16x16x32_bf16 v[32:35], v[108:111], v[100:103], v[32:35]
	v_mfma_f32_16x16x32_bf16 v[28:31], v[108:111], v[84:87], v[28:31]
	v_mfma_f32_16x16x32_bf16 v[32:35], v[112:115], v[104:107], v[32:35]
	v_mfma_f32_16x16x32_bf16 v[28:31], v[112:115], v[88:91], v[28:31]
	ds_read_b64 v[108:109], v0 offset:14336
	ds_read_b64 v[110:111], v2 offset:14336
	ds_read_b64 v[112:113], v3 offset:14336
	ds_read_b64 v[114:115], v173 offset:14336
	s_waitcnt lgkmcnt(8)
	v_mfma_f32_16x16x32_bf16 v[24:27], v[174:177], v[100:103], v[24:27]
	v_mfma_f32_16x16x32_bf16 v[16:19], v[174:177], v[84:87], v[16:19]
	v_mfma_f32_16x16x32_bf16 v[24:27], v[178:181], v[104:107], v[24:27]
	v_mfma_f32_16x16x32_bf16 v[16:19], v[178:181], v[88:91], v[16:19]
	s_waitcnt lgkmcnt(4)
	v_mfma_f32_16x16x32_bf16 v[20:23], v[92:95], v[100:103], v[20:23]
	v_mfma_f32_16x16x32_bf16 v[8:11], v[92:95], v[84:87], v[8:11]
	v_mfma_f32_16x16x32_bf16 v[20:23], v[96:99], v[104:107], v[20:23]
	v_mfma_f32_16x16x32_bf16 v[8:11], v[96:99], v[88:91], v[8:11]
	s_waitcnt lgkmcnt(0)
	v_mfma_f32_16x16x32_bf16 v[12:15], v[108:111], v[100:103], v[12:15]
	s_cmp_lg_u32 s6, 3
	s_cselect_b32 s6, s10, 0
	v_mfma_f32_16x16x32_bf16 v[2:5], v[108:111], v[84:87], v[4:7]
	v_mfma_f32_16x16x32_bf16 v[12:15], v[112:115], v[104:107], v[12:15]
	v_mfma_f32_16x16x32_bf16 v[4:7], v[112:115], v[88:91], v[2:5]
	v_lshl_add_u64 v[122:123], v[122:123], 0, s[30:31]
	v_lshl_add_u64 v[124:125], v[124:125], 0, s[30:31]
	v_lshl_add_u64 v[126:127], v[126:127], 0, s[46:47]
	s_cmp_eq_u32 s8, 19
	v_lshl_add_u64 v[128:129], v[128:129], 0, s[46:47]
	s_cbranch_scc1 .LBB0_161

.Lat_b_loop:
	s_waitcnt vmcnt(4)
	s_barrier
	s_cmp_gt_u32 s8, 17
	s_cbranch_scc1 .Lat_b_157
	s_lshl_b32 s9, s6, 15
	s_add_i32 s9, s9, 0
	v_add_u32_e32 v0, s9, v162
	v_add_u32_e32 v182, s9, v164
	v_readfirstlane_b32 s10, v0
	v_lshl_add_u64 v[2:3], s[48:49], 0, v[126:127]
	s_mov_b32 m0, s10
	v_readfirstlane_b32 s9, v182
	v_add_u32_e32 v0, 0x4000, v0
	global_load_lds_dwordx4 v[2:3], off
	v_lshl_add_u64 v[2:3], s[48:49], 0, v[128:129]
	s_mov_b32 m0, s9
	v_readfirstlane_b32 s9, v0
	v_add_u32_e32 v0, 0x4000, v182
	global_load_lds_dwordx4 v[2:3], off
	v_lshl_add_u64 v[2:3], s[48:49], 0, v[124:125]
	s_mov_b32 m0, s9
	v_readfirstlane_b32 s9, v0
	global_load_lds_dwordx4 v[2:3], off
	v_lshl_add_u64 v[2:3], s[48:49], 0, v[122:123]
	s_mov_b32 m0, s9
	s_nop 0
	global_load_lds_dwordx4 v[2:3], off
.Lat_b_157:
	s_cmp_eq_u32 s8, 0
	s_cbranch_scc1 .Lat_b_qk
	s_add_i32 s9, s7, 3
	s_and_b32 s9, s9, 3
	s_lshl_b32 s9, s9, 15
	v_add_u32_e32 v0, s9, v117
	ds_read_b64 v[92:93], v0 offset:0
	v_add_u32_e32 v2, s9, v137
	ds_read_b64 v[94:95], v2 offset:0
	v_add_u32_e32 v3, s9, v138
	ds_read_b64 v[96:97], v3 offset:0
	v_add_u32_e32 v173, s9, v139
	ds_read_b64 v[98:99], v173 offset:0
	ds_read_b64 v[108:109], v0 offset:2048
	ds_read_b64 v[110:111], v2 offset:2048
	ds_read_b64 v[112:113], v3 offset:2048
	ds_read_b64 v[114:115], v173 offset:2048
	ds_read_b64 v[174:175], v0 offset:4096
	ds_read_b64 v[176:177], v2 offset:4096
	ds_read_b64 v[178:179], v3 offset:4096
	ds_read_b64 v[180:181], v173 offset:4096
	s_waitcnt lgkmcnt(8)
	v_mfma_f32_16x16x32_bf16 v[64:67], v[92:95], v[100:103], v[64:67]
	v_mfma_f32_16x16x32_bf16 v[60:63], v[92:95], v[84:87], v[60:63]
	v_mfma_f32_16x16x32_bf16 v[64:67], v[96:99], v[104:107], v[64:67]
	v_mfma_f32_16x16x32_bf16 v[60:63], v[96:99], v[88:91], v[60:63]
	ds_read_b64 v[92:93], v0 offset:6144
	ds_read_b64 v[94:95], v2 offset:6144
	ds_read_b64 v[96:97], v3 offset:6144
	ds_read_b64 v[98:99], v173 offset:6144
	s_waitcnt lgkmcnt(8)
	v_mfma_f32_16x16x32_bf16 v[56:59], v[108:111], v[100:103], v[56:59]
	v_mfma_f32_16x16x32_bf16 v[52:55], v[108:111], v[84:87], v[52:55]
	v_mfma_f32_16x16x32_bf16 v[56:59], v[112:115], v[104:107], v[56:59]
	v_mfma_f32_16x16x32_bf16 v[52:55], v[112:115], v[88:91], v[52:55]
	ds_read_b64 v[108:109], v0 offset:8192
	ds_read_b64 v[110:111], v2 offset:8192
	ds_read_b64 v[112:113], v3 offset:8192
	ds_read_b64 v[114:115], v173 offset:8192
	s_waitcnt lgkmcnt(8)
	v_mfma_f32_16x16x32_bf16 v[48:51], v[174:177], v[100:103], v[48:51]
	v_mfma_f32_16x16x32_bf16 v[44:47], v[174:177], v[84:87], v[44:47]
	v_mfma_f32_16x16x32_bf16 v[48:51], v[178:181], v[104:107], v[48:51]
	v_mfma_f32_16x16x32_bf16 v[44:47], v[178:181], v[88:91], v[44:47]
	ds_read_b64 v[174:175], v0 offset:10240
	ds_read_b64 v[176:177], v2 offset:10240
	ds_read_b64 v[178:179], v3 offset:10240
	ds_read_b64 v[180:181], v173 offset:10240
	s_waitcnt lgkmcnt(8)
	v_mfma_f32_16x16x32_bf16 v[40:43], v[92:95], v[100:103], v[40:43]
	v_mfma_f32_16x16x32_bf16 v[36:39], v[92:95], v[84:87], v[36:39]
	v_mfma_f32_16x16x32_bf16 v[40:43], v[96:99], v[104:107], v[40:43]
	v_mfma_f32_16x16x32_bf16 v[36:39], v[96:99], v[88:91], v[36:39]
	ds_read_b64 v[92:93], v0 offset:12288
	ds_read_b64 v[94:95], v2 offset:12288
	ds_read_b64 v[96:97], v3 offset:12288
	ds_read_b64 v[98:99], v173 offset:12288
	s_waitcnt lgkmcnt(8)
	v_mfma_f32_16x16x32_bf16 v[32:35], v[108:111], v[100:103], v[32:35]
	v_mfma_f32_16x16x32_bf16 v[28:31], v[108:111], v[84:87], v[28:31]
	v_mfma_f32_16x16x32_bf16 v[32:35], v[112:115], v[104:107], v[32:35]
	v_mfma_f32_16x16x32_bf16 v[28:31], v[112:115], v[88:91], v[28:31]
	ds_read_b64 v[108:109], v0 offset:14336
	ds_read_b64 v[110:111], v2 offset:14336
	ds_read_b64 v[112:113], v3 offset:14336
	ds_read_b64 v[114:115], v173 offset:14336
	s_waitcnt lgkmcnt(8)
	v_mfma_f32_16x16x32_bf16 v[24:27], v[174:177], v[100:103], v[24:27]
	v_mfma_f32_16x16x32_bf16 v[16:19], v[174:177], v[84:87], v[16:19]
	v_mfma_f32_16x16x32_bf16 v[24:27], v[178:181], v[104:107], v[24:27]
	v_mfma_f32_16x16x32_bf16 v[16:19], v[178:181], v[88:91], v[16:19]
	s_waitcnt lgkmcnt(4)
	v_mfma_f32_16x16x32_bf16 v[20:23], v[92:95], v[100:103], v[20:23]
	v_mfma_f32_16x16x32_bf16 v[8:11], v[92:95], v[84:87], v[8:11]
	v_mfma_f32_16x16x32_bf16 v[20:23], v[96:99], v[104:107], v[20:23]
	v_mfma_f32_16x16x32_bf16 v[8:11], v[96:99], v[88:91], v[8:11]
	s_waitcnt lgkmcnt(0)
	v_mfma_f32_16x16x32_bf16 v[12:15], v[108:111], v[100:103], v[12:15]
	v_mfma_f32_16x16x32_bf16 v[2:5], v[108:111], v[84:87], v[4:7]
	v_mfma_f32_16x16x32_bf16 v[12:15], v[112:115], v[104:107], v[12:15]
	v_mfma_f32_16x16x32_bf16 v[4:7], v[112:115], v[88:91], v[2:5]
	s_nop 7

.Lat_b_E:
	v_sub_f32_e32 v0, v112, v163
	v_exp_f32_e32 v0, v0
	v_sub_f32_e32 v2, v113, v163
	v_exp_f32_e32 v2, v2
	v_sub_f32_e32 v3, v114, v163
	v_exp_f32_e32 v3, v3
	v_sub_f32_e32 v112, v115, v163
	v_exp_f32_e32 v112, v112
	v_sub_f32_e32 v108, v108, v163
	v_add_f32_e32 v113, 0, v0
	v_exp_f32_e32 v108, v108
	v_sub_f32_e32 v109, v109, v163
	v_add_f32_e32 v113, v2, v113
	v_exp_f32_e32 v109, v109
	v_sub_f32_e32 v110, v110, v163
	v_add_f32_e32 v113, v3, v113
	v_exp_f32_e32 v110, v110
	v_sub_f32_e32 v111, v111, v163
	v_add_f32_e32 v113, v112, v113
	v_exp_f32_e32 v111, v111
	v_sub_f32_e32 v104, v104, v163
	v_add_f32_e32 v113, v108, v113
	v_exp_f32_e32 v104, v104
	v_sub_f32_e32 v105, v105, v163
	v_add_f32_e32 v113, v109, v113
	v_exp_f32_e32 v105, v105
	v_sub_f32_e32 v106, v106, v163
	v_add_f32_e32 v113, v110, v113
	v_exp_f32_e32 v106, v106
	v_sub_f32_e32 v107, v107, v163
	v_add_f32_e32 v113, v111, v113
	v_exp_f32_e32 v107, v107
	v_sub_f32_e32 v100, v100, v163
	v_add_f32_e32 v113, v104, v113
	v_exp_f32_e32 v114, v100
	v_sub_f32_e32 v100, v101, v163
	v_add_f32_e32 v113, v105, v113
	v_exp_f32_e32 v115, v100
	v_sub_f32_e32 v100, v102, v163
	v_add_f32_e32 v113, v106, v113
	v_exp_f32_e32 v173, v100
	v_sub_f32_e32 v100, v103, v163
	v_add_f32_e32 v113, v107, v113
	v_exp_f32_e32 v174, v100
	v_add_f32_e32 v100, v114, v113
	v_add_f32_e32 v100, v115, v100
	v_add_f32_e32 v100, v173, v100
	v_add_f32_e32 v100, v174, v100
	v_add_f32_e32 v141, v141, v100
	v_cvt_pk_bf16_f32 v100, v0, v2
	v_sub_f32_e32 v0, v96, v161
	v_exp_f32_e32 v0, v0
	v_sub_f32_e32 v2, v97, v161
	v_cvt_pk_bf16_f32 v101, v3, v112
	v_exp_f32_e32 v2, v2
	v_sub_f32_e32 v3, v98, v161
	v_exp_f32_e32 v3, v3
	v_sub_f32_e32 v96, v99, v161
	v_exp_f32_e32 v96, v96
	v_sub_f32_e32 v92, v92, v161
	v_add_f32_e32 v97, 0, v0
	v_exp_f32_e32 v92, v92
	v_sub_f32_e32 v93, v93, v161
	v_add_f32_e32 v97, v2, v97
	v_exp_f32_e32 v93, v93
	v_sub_f32_e32 v94, v94, v161
	v_add_f32_e32 v97, v3, v97
	v_exp_f32_e32 v94, v94
	v_sub_f32_e32 v95, v95, v161
	v_add_f32_e32 v97, v96, v97
	v_exp_f32_e32 v95, v95
	v_sub_f32_e32 v88, v88, v161
	v_add_f32_e32 v97, v92, v97
	v_exp_f32_e32 v88, v88
	v_sub_f32_e32 v89, v89, v161
	v_add_f32_e32 v97, v93, v97
	v_exp_f32_e32 v89, v89
	v_sub_f32_e32 v90, v90, v161
	v_add_f32_e32 v97, v94, v97
	v_exp_f32_e32 v90, v90
	v_sub_f32_e32 v91, v91, v161
	v_add_f32_e32 v97, v95, v97
	v_exp_f32_e32 v91, v91
	v_sub_f32_e32 v84, v84, v161
	v_add_f32_e32 v97, v88, v97
	v_exp_f32_e32 v98, v84
	v_sub_f32_e32 v84, v85, v161
	v_add_f32_e32 v97, v89, v97
	v_exp_f32_e32 v99, v84
	v_sub_f32_e32 v84, v86, v161
	v_cvt_pk_bf16_f32 v102, v108, v109
	v_add_f32_e32 v97, v90, v97
	v_exp_f32_e32 v108, v84
	v_sub_f32_e32 v84, v87, v161
	v_add_f32_e32 v97, v91, v97
	v_exp_f32_e32 v109, v84
	v_add_f32_e32 v84, v98, v97
	v_add_f32_e32 v84, v99, v84
	v_add_f32_e32 v84, v108, v84
	v_add_f32_e32 v84, v109, v84
	v_add_f32_e32 v140, v140, v84
	v_cvt_pk_bf16_f32 v84, v0, v2
	v_cvt_pk_bf16_f32 v86, v92, v93
	v_cvt_pk_bf16_f32 v87, v94, v95
	v_cvt_pk_bf16_f32 v85, v3, v96
	v_cvt_pk_bf16_f32 v104, v104, v105
	v_cvt_pk_bf16_f32 v105, v106, v107
	v_cvt_pk_bf16_f32 v107, v173, v174
	v_cvt_pk_bf16_f32 v88, v88, v89
	v_cvt_pk_bf16_f32 v89, v90, v91
	v_cvt_pk_bf16_f32 v90, v98, v99
	v_cvt_pk_bf16_f32 v91, v108, v109
	v_cvt_pk_bf16_f32 v103, v110, v111
	v_cvt_pk_bf16_f32 v106, v114, v115
	s_add_i32 s10, s7, 1
	s_cmp_lg_u32 s7, 3
	s_cselect_b32 s7, s10, 0
	s_add_i32 s8, s8, 1
	s_add_i32 s10, s6, 1
	s_cmp_lg_u32 s6, 3
	s_cselect_b32 s6, s10, 0
	v_lshl_add_u64 v[122:123], v[122:123], 0, s[30:31]
	v_lshl_add_u64 v[124:125], v[124:125], 0, s[30:31]
	v_lshl_add_u64 v[126:127], v[126:127], 0, s[46:47]
	v_lshl_add_u64 v[128:129], v[128:129], 0, s[46:47]
	s_cmp_eq_u32 s8, 19
	s_cbranch_scc0 .Lat_b_loop
	s_add_i32 s9, s7, 3
	s_and_b32 s9, s9, 3
	s_lshl_b32 s9, s9, 15
	v_add_u32_e32 v0, s9, v117
	ds_read_b64 v[92:93], v0 offset:0
	v_add_u32_e32 v2, s9, v137
	ds_read_b64 v[94:95], v2 offset:0
	v_add_u32_e32 v3, s9, v138
	ds_read_b64 v[96:97], v3 offset:0
	v_add_u32_e32 v173, s9, v139
	ds_read_b64 v[98:99], v173 offset:0
	ds_read_b64 v[108:109], v0 offset:2048
	ds_read_b64 v[110:111], v2 offset:2048
	ds_read_b64 v[112:113], v3 offset:2048
	ds_read_b64 v[114:115], v173 offset:2048
	ds_read_b64 v[174:175], v0 offset:4096
	ds_read_b64 v[176:177], v2 offset:4096
	ds_read_b64 v[178:179], v3 offset:4096
	ds_read_b64 v[180:181], v173 offset:4096
	s_waitcnt lgkmcnt(8)
	v_mfma_f32_16x16x32_bf16 v[64:67], v[92:95], v[100:103], v[64:67]
	v_mfma_f32_16x16x32_bf16 v[60:63], v[92:95], v[84:87], v[60:63]
	v_mfma_f32_16x16x32_bf16 v[64:67], v[96:99], v[104:107], v[64:67]
	v_mfma_f32_16x16x32_bf16 v[60:63], v[96:99], v[88:91], v[60:63]
	ds_read_b64 v[92:93], v0 offset:6144
	ds_read_b64 v[94:95], v2 offset:6144
	ds_read_b64 v[96:97], v3 offset:6144
	ds_read_b64 v[98:99], v173 offset:6144
	s_waitcnt lgkmcnt(8)
	v_mfma_f32_16x16x32_bf16 v[56:59], v[108:111], v[100:103], v[56:59]
	v_mfma_f32_16x16x32_bf16 v[52:55], v[108:111], v[84:87], v[52:55]
	v_mfma_f32_16x16x32_bf16 v[56:59], v[112:115], v[104:107], v[56:59]
	v_mfma_f32_16x16x32_bf16 v[52:55], v[112:115], v[88:91], v[52:55]
	ds_read_b64 v[108:109], v0 offset:8192
	ds_read_b64 v[110:111], v2 offset:8192
	ds_read_b64 v[112:113], v3 offset:8192
	ds_read_b64 v[114:115], v173 offset:8192
	s_waitcnt lgkmcnt(8)
	v_mfma_f32_16x16x32_bf16 v[48:51], v[174:177], v[100:103], v[48:51]
	v_mfma_f32_16x16x32_bf16 v[44:47], v[174:177], v[84:87], v[44:47]
	v_mfma_f32_16x16x32_bf16 v[48:51], v[178:181], v[104:107], v[48:51]
	v_mfma_f32_16x16x32_bf16 v[44:47], v[178:181], v[88:91], v[44:47]
	ds_read_b64 v[174:175], v0 offset:10240
	ds_read_b64 v[176:177], v2 offset:10240
	ds_read_b64 v[178:179], v3 offset:10240
	ds_read_b64 v[180:181], v173 offset:10240
	s_waitcnt lgkmcnt(8)
	v_mfma_f32_16x16x32_bf16 v[40:43], v[92:95], v[100:103], v[40:43]
	v_mfma_f32_16x16x32_bf16 v[36:39], v[92:95], v[84:87], v[36:39]
	v_mfma_f32_16x16x32_bf16 v[40:43], v[96:99], v[104:107], v[40:43]
	v_mfma_f32_16x16x32_bf16 v[36:39], v[96:99], v[88:91], v[36:39]
	ds_read_b64 v[92:93], v0 offset:12288
	ds_read_b64 v[94:95], v2 offset:12288
	ds_read_b64 v[96:97], v3 offset:12288
	ds_read_b64 v[98:99], v173 offset:12288
	s_waitcnt lgkmcnt(8)
	v_mfma_f32_16x16x32_bf16 v[32:35], v[108:111], v[100:103], v[32:35]
	v_mfma_f32_16x16x32_bf16 v[28:31], v[108:111], v[84:87], v[28:31]
	v_mfma_f32_16x16x32_bf16 v[32:35], v[112:115], v[104:107], v[32:35]
	v_mfma_f32_16x16x32_bf16 v[28:31], v[112:115], v[88:91], v[28:31]
	ds_read_b64 v[108:109], v0 offset:14336
	ds_read_b64 v[110:111], v2 offset:14336
	ds_read_b64 v[112:113], v3 offset:14336
	ds_read_b64 v[114:115], v173 offset:14336
	s_waitcnt lgkmcnt(8)
	v_mfma_f32_16x16x32_bf16 v[24:27], v[174:177], v[100:103], v[24:27]
	v_mfma_f32_16x16x32_bf16 v[16:19], v[174:177], v[84:87], v[16:19]
	v_mfma_f32_16x16x32_bf16 v[24:27], v[178:181], v[104:107], v[24:27]
	v_mfma_f32_16x16x32_bf16 v[16:19], v[178:181], v[88:91], v[16:19]
	s_waitcnt lgkmcnt(4)
	v_mfma_f32_16x16x32_bf16 v[20:23], v[92:95], v[100:103], v[20:23]
	v_mfma_f32_16x16x32_bf16 v[8:11], v[92:95], v[84:87], v[8:11]
	v_mfma_f32_16x16x32_bf16 v[20:23], v[96:99], v[104:107], v[20:23]
	v_mfma_f32_16x16x32_bf16 v[8:11], v[96:99], v[88:91], v[8:11]
	s_waitcnt lgkmcnt(0)
	v_mfma_f32_16x16x32_bf16 v[12:15], v[108:111], v[100:103], v[12:15]
	v_mfma_f32_16x16x32_bf16 v[2:5], v[108:111], v[84:87], v[4:7]
	v_mfma_f32_16x16x32_bf16 v[12:15], v[112:115], v[104:107], v[12:15]
	v_mfma_f32_16x16x32_bf16 v[4:7], v[112:115], v[88:91], v[2:5]
	s_nop 7
	s_nop 1
	s_branch .LBB0_161
.LBB0_161:
	v_cmp_lt_i32_e32 vcc, v154, v148
	s_waitcnt lgkmcnt(0)
	v_add_f32_e32 v0, v169, v172
	v_add_f32_e32 v3, v165, v170
	v_cndmask_b32_e32 v2, v147, v154, vcc
	v_lshlrev_b32_e32 v2, 2, v2
	ds_bpermute_b32 v104, v2, v3
	ds_bpermute_b32 v2, v2, v0
	s_waitcnt vmcnt(0)
	s_barrier
	v_add_u32_e32 v92, 0x18000, v166
	ds_read_b128 v[84:87], v92 offset:0
	v_add_u32_e32 v93, 0x18000, v167
	ds_read_b128 v[88:91], v93 offset:0
	ds_read_b128 v[96:99], v92 offset:4096
	ds_read_b128 v[100:103], v93 offset:4096
	ds_read_b128 v[106:109], v92 offset:8192
	ds_read_b128 v[110:113], v93 offset:8192
	ds_read_b128 v[122:125], v92 offset:12288
	ds_read_b128 v[126:129], v93 offset:12288
	v_add_u32_e32 v94, 0x18000, v168
	ds_read_b128 v[164:167], v94 offset:0
	v_add_u32_e32 v95, 0x18000, v171
	ds_read_b128 v[168:171], v95 offset:0
	ds_read_b128 v[172:175], v94 offset:4096
	ds_read_b128 v[176:179], v95 offset:4096
	ds_read_b128 v[180:183], v94 offset:8192
	ds_read_b128 v[184:187], v95 offset:8192
	ds_read_b128 v[188:191], v94 offset:12288
	ds_read_b128 v[192:195], v95 offset:12288
	s_waitcnt lgkmcnt(8)
	v_mfma_f32_16x16x32_bf16 v[84:87], v[84:87], v[76:79], 0
	v_mfma_f32_16x16x32_bf16 v[92:95], v[88:91], v[80:83], v[84:87]
	v_mfma_f32_16x16x32_bf16 v[84:87], v[96:99], v[76:79], 0
	v_mfma_f32_16x16x32_bf16 v[88:91], v[100:103], v[80:83], v[84:87]
	v_mfma_f32_16x16x32_bf16 v[84:87], v[106:109], v[76:79], 0
	v_mfma_f32_16x16x32_bf16 v[76:79], v[122:125], v[76:79], 0
	v_mfma_f32_16x16x32_bf16 v[100:103], v[110:113], v[80:83], v[84:87]
	v_mfma_f32_16x16x32_bf16 v[96:99], v[126:129], v[80:83], v[76:79]
	s_waitcnt lgkmcnt(0)
	v_mfma_f32_16x16x32_bf16 v[76:79], v[164:167], v[68:71], 0
	v_mfma_f32_16x16x32_bf16 v[84:87], v[168:171], v[72:75], v[76:79]
	v_mfma_f32_16x16x32_bf16 v[76:79], v[172:175], v[68:71], 0
	v_mfma_f32_16x16x32_bf16 v[80:83], v[176:179], v[72:75], v[76:79]
	v_mfma_f32_16x16x32_bf16 v[76:79], v[180:183], v[68:71], 0
	v_mfma_f32_16x16x32_bf16 v[68:71], v[188:191], v[68:71], 0
	v_mfma_f32_16x16x32_bf16 v[76:79], v[184:187], v[72:75], v[76:79]
	v_mfma_f32_16x16x32_bf16 v[68:71], v[192:195], v[72:75], v[68:71]
	v_max3_f32 v72, v92, s29, v93
	v_max3_f32 v72, v72, v94, v95
	v_max3_f32 v72, v72, v88, v89
	v_max3_f32 v72, v72, v90, v91
	v_max3_f32 v72, v72, v100, v101
	v_max3_f32 v72, v72, v102, v103
	v_max3_f32 v72, v72, v96, v97
	v_max3_f32 v72, v72, v98, v99
	v_add_f32_e32 v73, 0x41000000, v163
	v_cmp_gt_f32_e32 vcc, v72, v73
	s_cbranch_vccz .LBB0_163
	ds_bpermute_b32 v73, v136, v72
	v_max_f32_e32 v72, v72, v72
	s_waitcnt lgkmcnt(0)
	v_max_f32_e32 v73, v73, v73
	v_max_f32_e32 v72, v72, v73
	ds_bpermute_b32 v73, v135, v72
	s_waitcnt lgkmcnt(0)
	v_max3_f32 v73, v163, v72, v73
	v_sub_f32_e32 v72, v163, v73
	v_exp_f32_e32 v72, v72
	v_mov_b32_e32 v163, v73
	v_mul_f32_e32 v141, v141, v72
	v_pk_mul_f32 v[66:67], v[66:67], v[72:73] op_sel_hi:[1,0]
	v_pk_mul_f32 v[64:65], v[64:65], v[72:73] op_sel_hi:[1,0]
	v_pk_mul_f32 v[58:59], v[58:59], v[72:73] op_sel_hi:[1,0]
	v_pk_mul_f32 v[56:57], v[56:57], v[72:73] op_sel_hi:[1,0]
	v_pk_mul_f32 v[50:51], v[50:51], v[72:73] op_sel_hi:[1,0]
	v_pk_mul_f32 v[48:49], v[48:49], v[72:73] op_sel_hi:[1,0]
	v_pk_mul_f32 v[42:43], v[42:43], v[72:73] op_sel_hi:[1,0]
	v_pk_mul_f32 v[40:41], v[40:41], v[72:73] op_sel_hi:[1,0]
	v_pk_mul_f32 v[34:35], v[34:35], v[72:73] op_sel_hi:[1,0]
	v_pk_mul_f32 v[32:33], v[32:33], v[72:73] op_sel_hi:[1,0]
	v_pk_mul_f32 v[26:27], v[26:27], v[72:73] op_sel_hi:[1,0]
	v_pk_mul_f32 v[24:25], v[24:25], v[72:73] op_sel_hi:[1,0]
	v_pk_mul_f32 v[22:23], v[22:23], v[72:73] op_sel_hi:[1,0]
	v_pk_mul_f32 v[20:21], v[20:21], v[72:73] op_sel_hi:[1,0]
	v_pk_mul_f32 v[14:15], v[14:15], v[72:73] op_sel_hi:[1,0]
	v_pk_mul_f32 v[12:13], v[12:13], v[72:73] op_sel_hi:[1,0]
